# v21 + uq EpiGen rope sections: cos/sin table loads software-pipelined one row group ahead (two dead register banks), vmcnt(4) waits
# speedup vs baseline: 1.0006x; 1.0006x over previous
; __device__ __forceinline__ unsigned pk2(float lo, float hi) { f32x2_t v = {lo, hi}; bf16x2_t b = __builtin_convertvector(v, bf16x2_t); return __builtin_bit_cast(unsigned, b); }
; __device__ __forceinline__ float fast_sigmoid(float x) { return __builtin_amdgcn_rcpf(1.f + __expf(-x)); }
;     __device__ __forceinline__ void operator()(const f32x4 (&acc)[2][2][4][2], const Unit& u, int wr, int wc, int fr, int fq) const {
;     ...
;                     const int row = row0 + ai * HALF + m * 16; const float rs = rsv[ai][m] * scale;
;                     f32x4 v0 = acc[ai][bj][m][0] * rs, v1 = acc[ai][bj][m][1] * rs;
;                     if (rp) {
;                         const int pos = row & (SEQ - 1); const float* rb = rope + pos * 32 + 8 * (fq & 1); const bool hi2 = (fq >> 1) != 0;
;                         const f32x4 cs0 = *(const f32x4*)(rb), cs1 = *(const f32x4*)(rb + 4), sn0 = *(const f32x4*)(rb + 16), sn1 = *(const f32x4*)(rb + 20);
; #pragma unroll
;                         for (int e = 0; e < 4; ++e) { const float q0 = __shfl_xor(v0[e], 32), q1 = __shfl_xor(v1[e], 32);
;                             v0[e] = hi2 ? v0[e] * cs0[e] + q0 * sn0[e] : v0[e] * cs0[e] - q0 * sn0[e];
;                             v1[e] = hi2 ? v1[e] * cs1[e] + q1 * sn1[e] : v1[e] * cs1[e] - q1 * sn1[e]; } }
;                     if (sig) {
; #pragma unroll
;                         for (int e = 0; e < 4; ++e) { v0[e] = fast_sigmoid(v0[e]); v1[e] = fast_sigmoid(v1[e]); } }
;                     if (sq) { float s = (v0[0] * v0[0] + v0[1] * v0[1]) + (v0[2] * v0[2] + v0[3] * v0[3]) + (v1[0] * v1[0] + v1[1] * v1[1]) + (v1[2] * v1[2] + v1[3] * v1[3]);
;                         s += __shfl_xor(s, 16); s += __shfl_xor(s, 32); if (fq == 0) sq[(size_t)row * sqp] = s; }
;                     u32x4 w; w.x = pk2(v0[0], v0[1]); w.y = pk2(v0[2], v0[3]); w.z = pk2(v1[0], v1[1]); w.w = pk2(v1[2], v1[3]);
;                     *(u32x4*)(O + (size_t)row * ldc + c0 + 8 * fq) = w;
.LBB0_584:
	s_or_b64 exec, exec, s[18:19]
	v_mov_b32_e32 v202, v154
	v_add_f32_e32 v132, v177, v178
	v_pk_add_f32 v[130:131], v[134:135], v[130:131]
	v_fmamk_f32 v132, v132, 0x3b2aaaab, v239
	v_add_f32_e32 v130, v130, v131
	v_mul_f32_e32 v133, 0x4b800000, v132
	v_cmp_gt_f32_e32 vcc, s55, v132
	ds_bpermute_b32 v131, v176, v130
	s_lshl_b32 s4, s4, 8
	v_cndmask_b32_e32 v132, v132, v133, vcc
	v_rsq_f32_e32 v132, v132
	s_or_b32 s18, s4, s31
	s_mul_hi_i32 s4, s18, 0x2aaaaaab
	s_waitcnt lgkmcnt(0)
	v_add_f32_e32 v131, v130, v131
	s_lshr_b32 s6, s4, 31
	s_lshr_b32 s4, s4, 4
	v_mul_f32_e32 v133, 0x45800000, v132
	ds_bpermute_b32 v134, v168, v131
	s_add_i32 s4, s4, s6
	v_cndmask_b32_e32 v132, v132, v133, vcc
	s_mulk_i32 s4, 0x60
	s_sub_i32 s4, s18, s4
	v_mul_f32_e32 v130, 0x3e16c740, v132
	s_cmp_eq_u32 s4, 64
	v_pk_mul_f32 v[132:133], v[122:123], v[130:131] op_sel_hi:[1,0]
	v_lshlrev_b32_e32 v122, 7, v154
	s_cselect_b64 s[20:21], -1, 0
	s_cmp_lg_u32 s4, 64
	v_pk_mul_f32 v[128:129], v[128:129], v[130:131] op_sel_hi:[1,0]
	v_pk_mul_f32 v[126:127], v[126:127], v[130:131] op_sel_hi:[1,0]
	v_pk_mul_f32 v[124:125], v[124:125], v[130:131] op_sel_hi:[1,0]
	v_and_b32_e32 v122, 0x3e780, v122
	s_cbranch_scc1 .LBB0_586
	v_mov_b32_e32 v123, v1
	v_lshl_add_u64 v[164:165], v[148:149], 0, v[122:123]
	global_load_dwordx4 v[176:179], v[164:165], off offset:16
	global_load_dwordx4 v[180:183], v[164:165], off
	global_load_dwordx4 v[184:187], v[164:165], off offset:80
	global_load_dwordx4 v[188:191], v[164:165], off offset:64
	v_add_u32_e32 v194, 0x10, v202
	v_lshlrev_b32_e32 v194, 7, v194
	v_and_b32_e32 v194, 0x3ff80, v194
	v_mov_b32_e32 v195, v1
	v_lshl_add_u64 v[194:195], v[148:149], 0, v[194:195]
	global_load_dwordx4 v[222:225], v[194:195], off offset:16
	global_load_dwordx4 v[226:229], v[194:195], off
	global_load_dwordx4 v[230:233], v[194:195], off offset:80
	global_load_dwordx4 v[234:237], v[194:195], off offset:64
	ds_bpermute_b32 v164, v168, v126
	ds_bpermute_b32 v192, v168, v132
	ds_bpermute_b32 v165, v168, v127
	ds_bpermute_b32 v193, v168, v133
	s_waitcnt vmcnt(4) lgkmcnt(0)
	v_pk_mul_f32 v[184:185], v[184:185], v[192:193]
	v_pk_mul_f32 v[164:165], v[188:189], v[164:165]
	ds_bpermute_b32 v188, v168, v128
	ds_bpermute_b32 v192, v168, v124
	ds_bpermute_b32 v189, v168, v129
	ds_bpermute_b32 v193, v168, v125
	v_cndmask_b32_e64 v165, v165, -v165, s[46:47]
	v_cndmask_b32_e64 v164, v164, -v164, s[46:47]
	v_pk_fma_f32 v[126:127], v[126:127], v[180:181], v[164:165]
	s_waitcnt lgkmcnt(1)
	v_pk_mul_f32 v[188:189], v[190:191], v[188:189]
	s_waitcnt lgkmcnt(0)
	v_pk_mul_f32 v[164:165], v[186:187], v[192:193]
	v_cndmask_b32_e64 v189, v189, -v189, s[46:47]
	v_cndmask_b32_e64 v188, v188, -v188, s[46:47]
	v_cndmask_b32_e64 v165, v165, -v165, s[46:47]
	v_cndmask_b32_e64 v164, v164, -v164, s[46:47]
	v_cndmask_b32_e64 v181, v185, -v185, s[46:47]
	v_cndmask_b32_e64 v180, v184, -v184, s[46:47]
	v_pk_fma_f32 v[128:129], v[128:129], v[182:183], v[188:189]
	v_pk_fma_f32 v[124:125], v[124:125], v[178:179], v[164:165]
	v_pk_fma_f32 v[132:133], v[132:133], v[176:177], v[180:181]
.LBB0_586:
	v_add_f32_e32 v0, v0, v175
	v_fmamk_f32 v0, v0, 0x3b2aaaab, v239
	v_mul_f32_e32 v123, 0x4b800000, v0
	v_cmp_gt_f32_e32 vcc, s55, v0
	v_cvt_pk_bf16_f32 v179, v124, v125
	v_mov_b64_e32 v[124:125], s[58:59]
	v_cndmask_b32_e32 v0, v0, v123, vcc
	v_rsq_f32_e32 v0, v0
	s_movk_i32 s4, 0xc00
	s_ashr_i32 s19, s18, 31
	v_mad_i64_i32 v[124:125], s[6:7], v154, s4, v[124:125]
	v_mul_f32_e32 v123, 0x45800000, v0
	v_cndmask_b32_e32 v123, v0, v123, vcc
	v_lshl_add_u64 v[124:125], s[18:19], 1, v[124:125]
	v_lshlrev_b32_e32 v0, 1, v144
	v_cvt_pk_bf16_f32 v176, v126, v127
	v_lshl_add_u64 v[126:127], v[124:125], 0, v[0:1]
	v_mul_f32_e32 v124, 0x3e16c740, v123
	v_cvt_pk_bf16_f32 v177, v128, v129
	v_pk_mul_f32 v[128:129], v[114:115], v[124:125] op_sel_hi:[1,0]
	v_cndmask_b32_e64 v114, 0, 1, s[20:21]
	v_cmp_ne_u32_e64 s[50:51], 1, v114
	v_lshlrev_b32_e32 v114, 7, v162
	v_cvt_pk_bf16_f32 v178, v132, v133
	v_pk_mul_f32 v[120:121], v[120:121], v[124:125] op_sel_hi:[1,0]
	v_pk_mul_f32 v[118:119], v[118:119], v[124:125] op_sel_hi:[1,0]
	v_pk_mul_f32 v[116:117], v[116:117], v[124:125] op_sel_hi:[1,0]
	s_andn2_b64 vcc, exec, s[20:21]
	v_and_b32_e32 v114, 0x3ef80, v114
	global_store_dwordx4 v[126:127], v[176:179], off
	s_cbranch_vccnz .LBB0_588
	v_mov_b32_e32 v115, v1
	v_lshl_add_u64 v[132:133], v[148:149], 0, v[114:115]
	v_add_u32_e32 v194, 0x20, v202
	v_lshlrev_b32_e32 v194, 7, v194
	v_and_b32_e32 v194, 0x3ff80, v194
	v_mov_b32_e32 v195, v1
	v_lshl_add_u64 v[194:195], v[148:149], 0, v[194:195]
	global_load_dwordx4 v[206:209], v[194:195], off offset:16
	global_load_dwordx4 v[210:213], v[194:195], off
	global_load_dwordx4 v[214:217], v[194:195], off offset:80
	global_load_dwordx4 v[218:221], v[194:195], off offset:64
	ds_bpermute_b32 v132, v168, v118
	ds_bpermute_b32 v164, v168, v128
	ds_bpermute_b32 v133, v168, v119
	ds_bpermute_b32 v165, v168, v129
	s_waitcnt vmcnt(4) lgkmcnt(0)
	v_mov_b32_e32 v176, v222
	v_mov_b32_e32 v177, v223
	v_mov_b32_e32 v178, v224
	v_mov_b32_e32 v179, v225
	v_mov_b32_e32 v180, v226
	v_mov_b32_e32 v181, v227
	v_mov_b32_e32 v182, v228
	v_mov_b32_e32 v183, v229
	v_mov_b32_e32 v184, v230
	v_mov_b32_e32 v185, v231
	v_mov_b32_e32 v186, v232
	v_mov_b32_e32 v187, v233
	v_mov_b32_e32 v188, v234
	v_mov_b32_e32 v189, v235
	v_mov_b32_e32 v190, v236
	v_mov_b32_e32 v191, v237
	v_pk_mul_f32 v[164:165], v[184:185], v[164:165]
	v_pk_mul_f32 v[132:133], v[188:189], v[132:133]
	ds_bpermute_b32 v184, v168, v120
	ds_bpermute_b32 v188, v168, v116
	ds_bpermute_b32 v185, v168, v121
	ds_bpermute_b32 v189, v168, v117
	v_cndmask_b32_e64 v133, v133, -v133, s[46:47]
	v_cndmask_b32_e64 v132, v132, -v132, s[46:47]
	v_pk_fma_f32 v[118:119], v[118:119], v[180:181], v[132:133]
	s_waitcnt lgkmcnt(1)
	v_pk_mul_f32 v[184:185], v[190:191], v[184:185]
	s_waitcnt lgkmcnt(0)
	v_pk_mul_f32 v[132:133], v[186:187], v[188:189]
	v_cndmask_b32_e64 v185, v185, -v185, s[46:47]
	v_cndmask_b32_e64 v184, v184, -v184, s[46:47]
	v_cndmask_b32_e64 v133, v133, -v133, s[46:47]
	v_cndmask_b32_e64 v132, v132, -v132, s[46:47]
	v_cndmask_b32_e64 v165, v165, -v165, s[46:47]
	v_cndmask_b32_e64 v164, v164, -v164, s[46:47]
	v_pk_fma_f32 v[120:121], v[120:121], v[182:183], v[184:185]
	v_pk_fma_f32 v[116:117], v[116:117], v[178:179], v[132:133]
	v_pk_fma_f32 v[128:129], v[128:129], v[176:177], v[164:165]
; __device__ __forceinline__ unsigned pk2(float lo, float hi) { f32x2_t v = {lo, hi}; bf16x2_t b = __builtin_convertvector(v, bf16x2_t); return __builtin_bit_cast(unsigned, b); }
; __device__ __forceinline__ float fast_sigmoid(float x) { return __builtin_amdgcn_rcpf(1.f + __expf(-x)); }
;     __device__ __forceinline__ void operator()(const f32x4 (&acc)[2][2][4][2], const Unit& u, int wr, int wc, int fr, int fq) const {
;     ...
;                     const int row = row0 + ai * HALF + m * 16; const float rs = rsv[ai][m] * scale;
;                     f32x4 v0 = acc[ai][bj][m][0] * rs, v1 = acc[ai][bj][m][1] * rs;
;                     if (rp) {
;                         const int pos = row & (SEQ - 1); const float* rb = rope + pos * 32 + 8 * (fq & 1); const bool hi2 = (fq >> 1) != 0;
;                         const f32x4 cs0 = *(const f32x4*)(rb), cs1 = *(const f32x4*)(rb + 4), sn0 = *(const f32x4*)(rb + 16), sn1 = *(const f32x4*)(rb + 20);
; #pragma unroll
;                         for (int e = 0; e < 4; ++e) { const float q0 = __shfl_xor(v0[e], 32), q1 = __shfl_xor(v1[e], 32);
;                             v0[e] = hi2 ? v0[e] * cs0[e] + q0 * sn0[e] : v0[e] * cs0[e] - q0 * sn0[e];
;                             v1[e] = hi2 ? v1[e] * cs1[e] + q1 * sn1[e] : v1[e] * cs1[e] - q1 * sn1[e]; } }
;                     if (sig) {
; #pragma unroll
;                         for (int e = 0; e < 4; ++e) { v0[e] = fast_sigmoid(v0[e]); v1[e] = fast_sigmoid(v1[e]); } }
;                     if (sq) { float s = (v0[0] * v0[0] + v0[1] * v0[1]) + (v0[2] * v0[2] + v0[3] * v0[3]) + (v1[0] * v1[0] + v1[1] * v1[1]) + (v1[2] * v1[2] + v1[3] * v1[3]);
;                         s += __shfl_xor(s, 16); s += __shfl_xor(s, 32); if (fq == 0) sq[(size_t)row * sqp] = s; }
;                     u32x4 w; w.x = pk2(v0[0], v0[1]); w.y = pk2(v0[2], v0[3]); w.z = pk2(v1[0], v1[1]); w.w = pk2(v1[2], v1[3]);
;                     *(u32x4*)(O + (size_t)row * ldc + c0 + 8 * fq) = w;
.LBB0_588:
	v_add_f32_e32 v115, v173, v174
	v_fmamk_f32 v115, v115, 0x3b2aaaab, v239
	v_mul_f32_e32 v123, 0x4b800000, v115
	v_cmp_gt_f32_e32 vcc, s55, v115
	v_cvt_pk_bf16_f32 v177, v116, v117
	v_mov_b64_e32 v[116:117], s[58:59]
	v_cndmask_b32_e32 v115, v115, v123, vcc
	v_rsq_f32_e32 v115, v115
	v_cvt_pk_bf16_f32 v174, v118, v119
	v_mad_i64_i32 v[116:117], s[6:7], v162, s4, v[116:117]
	v_mul_f32_e32 v118, 0x45800000, v115
	v_cndmask_b32_e32 v115, v115, v118, vcc
	v_lshl_add_u64 v[116:117], s[18:19], 1, v[116:117]
	v_lshl_add_u64 v[118:119], v[116:117], 0, v[0:1]
	v_mul_f32_e32 v116, 0x3e16c740, v115
	v_cvt_pk_bf16_f32 v175, v120, v121
	v_pk_mul_f32 v[120:121], v[106:107], v[116:117] op_sel_hi:[1,0]
	v_lshlrev_b32_e32 v106, 7, v160
	v_cvt_pk_bf16_f32 v176, v128, v129
	v_pk_mul_f32 v[112:113], v[112:113], v[116:117] op_sel_hi:[1,0]
	v_pk_mul_f32 v[110:111], v[110:111], v[116:117] op_sel_hi:[1,0]
	v_pk_mul_f32 v[108:109], v[108:109], v[116:117] op_sel_hi:[1,0]
	s_and_b64 vcc, exec, s[50:51]
	v_and_b32_e32 v106, 0x3f780, v106
	global_store_dwordx4 v[118:119], v[174:177], off
	s_cbranch_vccnz .LBB0_590
	v_mov_b32_e32 v107, v1
	v_lshl_add_u64 v[128:129], v[148:149], 0, v[106:107]
	v_add_u32_e32 v194, 0x30, v202
	v_lshlrev_b32_e32 v194, 7, v194
	v_and_b32_e32 v194, 0x3ff80, v194
	v_mov_b32_e32 v195, v1
	v_lshl_add_u64 v[194:195], v[148:149], 0, v[194:195]
	global_load_dwordx4 v[222:225], v[194:195], off offset:16
	global_load_dwordx4 v[226:229], v[194:195], off
	global_load_dwordx4 v[230:233], v[194:195], off offset:80
	global_load_dwordx4 v[234:237], v[194:195], off offset:64
	ds_bpermute_b32 v132, v168, v120
	ds_bpermute_b32 v133, v168, v121
	ds_bpermute_b32 v128, v168, v110
	ds_bpermute_b32 v129, v168, v111
	ds_bpermute_b32 v164, v168, v112
	ds_bpermute_b32 v165, v168, v113
	s_waitcnt vmcnt(4) lgkmcnt(0)
	v_mov_b32_e32 v174, v206
	v_mov_b32_e32 v175, v207
	v_mov_b32_e32 v176, v208
	v_mov_b32_e32 v177, v209
	v_mov_b32_e32 v178, v210
	v_mov_b32_e32 v179, v211
	v_mov_b32_e32 v180, v212
	v_mov_b32_e32 v181, v213
	v_mov_b32_e32 v182, v214
	v_mov_b32_e32 v183, v215
	v_mov_b32_e32 v184, v216
	v_mov_b32_e32 v185, v217
	v_mov_b32_e32 v186, v218
	v_mov_b32_e32 v187, v219
	v_mov_b32_e32 v188, v220
	v_mov_b32_e32 v189, v221
	v_pk_mul_f32 v[132:133], v[182:183], v[132:133]
	ds_bpermute_b32 v182, v168, v108
	ds_bpermute_b32 v183, v168, v109
	v_pk_mul_f32 v[128:129], v[186:187], v[128:129]
	v_pk_mul_f32 v[164:165], v[188:189], v[164:165]
	v_cndmask_b32_e64 v129, v129, -v129, s[46:47]
	v_cndmask_b32_e64 v128, v128, -v128, s[46:47]
	v_pk_fma_f32 v[110:111], v[110:111], v[178:179], v[128:129]
	s_waitcnt lgkmcnt(0)
	v_pk_mul_f32 v[128:129], v[184:185], v[182:183]
	v_cndmask_b32_e64 v165, v165, -v165, s[46:47]
	v_cndmask_b32_e64 v164, v164, -v164, s[46:47]
	v_cndmask_b32_e64 v129, v129, -v129, s[46:47]
	v_cndmask_b32_e64 v128, v128, -v128, s[46:47]
	v_cndmask_b32_e64 v133, v133, -v133, s[46:47]
	v_cndmask_b32_e64 v132, v132, -v132, s[46:47]
	v_pk_fma_f32 v[112:113], v[112:113], v[180:181], v[164:165]
	v_pk_fma_f32 v[108:109], v[108:109], v[176:177], v[128:129]
	v_pk_fma_f32 v[120:121], v[120:121], v[174:175], v[132:133]
.LBB0_590:
	v_add_f32_e32 v107, v171, v172
	v_fmamk_f32 v107, v107, 0x3b2aaaab, v239
	v_mul_f32_e32 v115, 0x4b800000, v107
	v_cmp_gt_f32_e32 vcc, s55, v107
	v_cvt_pk_bf16_f32 v175, v108, v109
	v_mov_b64_e32 v[108:109], s[58:59]
	v_cndmask_b32_e32 v107, v107, v115, vcc
	v_rsq_f32_e32 v107, v107
	v_cvt_pk_bf16_f32 v172, v110, v111
	v_mad_i64_i32 v[108:109], s[6:7], v160, s4, v[108:109]
	v_mul_f32_e32 v110, 0x45800000, v107
	v_cndmask_b32_e32 v107, v107, v110, vcc
	v_lshl_add_u64 v[108:109], s[18:19], 1, v[108:109]
	v_lshl_add_u64 v[110:111], v[108:109], 0, v[0:1]
	v_mul_f32_e32 v108, 0x3e16c740, v107
	v_cvt_pk_bf16_f32 v173, v112, v113
	v_pk_mul_f32 v[112:113], v[98:99], v[108:109] op_sel_hi:[1,0]
	v_lshlrev_b32_e32 v98, 7, v158
	v_cvt_pk_bf16_f32 v174, v120, v121
	v_pk_mul_f32 v[104:105], v[104:105], v[108:109] op_sel_hi:[1,0]
	v_pk_mul_f32 v[102:103], v[102:103], v[108:109] op_sel_hi:[1,0]
	v_pk_mul_f32 v[100:101], v[100:101], v[108:109] op_sel_hi:[1,0]
	s_and_b64 vcc, exec, s[50:51]
	v_and_b32_e32 v98, 0x3ff80, v98
	global_store_dwordx4 v[110:111], v[172:175], off
	s_cbranch_vccnz .LBB0_592
	v_mov_b32_e32 v99, v1
	v_lshl_add_u64 v[120:121], v[148:149], 0, v[98:99]
	v_add_u32_e32 v194, 0x80, v202
	v_lshlrev_b32_e32 v194, 7, v194
	v_and_b32_e32 v194, 0x3ff80, v194
	v_mov_b32_e32 v195, v1
	v_lshl_add_u64 v[194:195], v[148:149], 0, v[194:195]
	global_load_dwordx4 v[206:209], v[194:195], off offset:16
	global_load_dwordx4 v[210:213], v[194:195], off
	global_load_dwordx4 v[214:217], v[194:195], off offset:80
	global_load_dwordx4 v[218:221], v[194:195], off offset:64
	ds_bpermute_b32 v120, v168, v102
	ds_bpermute_b32 v121, v168, v103
	ds_bpermute_b32 v128, v168, v112
	ds_bpermute_b32 v129, v168, v113
	ds_bpermute_b32 v132, v168, v104
	ds_bpermute_b32 v164, v168, v100
	ds_bpermute_b32 v133, v168, v105
	ds_bpermute_b32 v165, v168, v101
	s_waitcnt vmcnt(4) lgkmcnt(0)
	v_mov_b32_e32 v172, v222
	v_mov_b32_e32 v173, v223
	v_mov_b32_e32 v174, v224
	v_mov_b32_e32 v175, v225
	v_mov_b32_e32 v176, v226
	v_mov_b32_e32 v177, v227
	v_mov_b32_e32 v178, v228
	v_mov_b32_e32 v179, v229
	v_mov_b32_e32 v180, v230
	v_mov_b32_e32 v181, v231
	v_mov_b32_e32 v182, v232
	v_mov_b32_e32 v183, v233
	v_mov_b32_e32 v184, v234
	v_mov_b32_e32 v185, v235
	v_mov_b32_e32 v186, v236
	v_mov_b32_e32 v187, v237
	v_pk_mul_f32 v[128:129], v[180:181], v[128:129]
	v_pk_mul_f32 v[120:121], v[184:185], v[120:121]
	v_pk_mul_f32 v[132:133], v[186:187], v[132:133]
	v_cndmask_b32_e64 v121, v121, -v121, s[46:47]
	v_cndmask_b32_e64 v120, v120, -v120, s[46:47]
	v_pk_fma_f32 v[102:103], v[102:103], v[176:177], v[120:121]
	v_pk_mul_f32 v[120:121], v[182:183], v[164:165]
	v_cndmask_b32_e64 v133, v133, -v133, s[46:47]
	v_cndmask_b32_e64 v132, v132, -v132, s[46:47]
	v_cndmask_b32_e64 v121, v121, -v121, s[46:47]
	v_cndmask_b32_e64 v120, v120, -v120, s[46:47]
	v_cndmask_b32_e64 v129, v129, -v129, s[46:47]
	v_cndmask_b32_e64 v128, v128, -v128, s[46:47]
	v_pk_fma_f32 v[104:105], v[104:105], v[178:179], v[132:133]
	v_pk_fma_f32 v[100:101], v[100:101], v[174:175], v[120:121]
	v_pk_fma_f32 v[112:113], v[112:113], v[172:173], v[128:129]
; __device__ __forceinline__ unsigned pk2(float lo, float hi) { f32x2_t v = {lo, hi}; bf16x2_t b = __builtin_convertvector(v, bf16x2_t); return __builtin_bit_cast(unsigned, b); }
; __device__ __forceinline__ float fast_sigmoid(float x) { return __builtin_amdgcn_rcpf(1.f + __expf(-x)); }
;     __device__ __forceinline__ void operator()(const f32x4 (&acc)[2][2][4][2], const Unit& u, int wr, int wc, int fr, int fq) const {
;     ...
;                     const int row = row0 + ai * HALF + m * 16; const float rs = rsv[ai][m] * scale;
;                     f32x4 v0 = acc[ai][bj][m][0] * rs, v1 = acc[ai][bj][m][1] * rs;
;                     if (rp) {
;                         const int pos = row & (SEQ - 1); const float* rb = rope + pos * 32 + 8 * (fq & 1); const bool hi2 = (fq >> 1) != 0;
;                         const f32x4 cs0 = *(const f32x4*)(rb), cs1 = *(const f32x4*)(rb + 4), sn0 = *(const f32x4*)(rb + 16), sn1 = *(const f32x4*)(rb + 20);
; #pragma unroll
;                         for (int e = 0; e < 4; ++e) { const float q0 = __shfl_xor(v0[e], 32), q1 = __shfl_xor(v1[e], 32);
;                             v0[e] = hi2 ? v0[e] * cs0[e] + q0 * sn0[e] : v0[e] * cs0[e] - q0 * sn0[e];
;                             v1[e] = hi2 ? v1[e] * cs1[e] + q1 * sn1[e] : v1[e] * cs1[e] - q1 * sn1[e]; } }
;                     if (sig) {
; #pragma unroll
;                         for (int e = 0; e < 4; ++e) { v0[e] = fast_sigmoid(v0[e]); v1[e] = fast_sigmoid(v1[e]); } }
;                     if (sq) { float s = (v0[0] * v0[0] + v0[1] * v0[1]) + (v0[2] * v0[2] + v0[3] * v0[3]) + (v1[0] * v1[0] + v1[1] * v1[1]) + (v1[2] * v1[2] + v1[3] * v1[3]);
;                         s += __shfl_xor(s, 16); s += __shfl_xor(s, 32); if (fq == 0) sq[(size_t)row * sqp] = s; }
;                     u32x4 w; w.x = pk2(v0[0], v0[1]); w.y = pk2(v0[2], v0[3]); w.z = pk2(v1[0], v1[1]); w.w = pk2(v1[2], v1[3]);
;                     *(u32x4*)(O + (size_t)row * ldc + c0 + 8 * fq) = w;
.LBB0_592:
	v_add_f32_e32 v99, v169, v170
	v_fmamk_f32 v99, v99, 0x3b2aaaab, v239
	v_mul_f32_e32 v107, 0x4b800000, v99
	v_cmp_gt_f32_e32 vcc, s55, v99
	v_cvt_pk_bf16_f32 v173, v100, v101
	v_mov_b64_e32 v[100:101], s[58:59]
	v_cndmask_b32_e32 v99, v99, v107, vcc
	v_rsq_f32_e32 v99, v99
	v_cvt_pk_bf16_f32 v170, v102, v103
	v_mad_i64_i32 v[100:101], s[6:7], v158, s4, v[100:101]
	v_mul_f32_e32 v102, 0x45800000, v99
	v_cndmask_b32_e32 v99, v99, v102, vcc
	v_lshl_add_u64 v[100:101], s[18:19], 1, v[100:101]
	v_lshl_add_u64 v[102:103], v[100:101], 0, v[0:1]
	v_mul_f32_e32 v100, 0x3e16c740, v99
	v_cvt_pk_bf16_f32 v171, v104, v105
	v_pk_mul_f32 v[104:105], v[90:91], v[100:101] op_sel_hi:[1,0]
	v_lshlrev_b32_e32 v90, 7, v156
	v_cvt_pk_bf16_f32 v172, v112, v113
	v_pk_mul_f32 v[96:97], v[96:97], v[100:101] op_sel_hi:[1,0]
	v_pk_mul_f32 v[94:95], v[94:95], v[100:101] op_sel_hi:[1,0]
	v_pk_mul_f32 v[92:93], v[92:93], v[100:101] op_sel_hi:[1,0]
	s_and_b64 vcc, exec, s[50:51]
	v_and_b32_e32 v90, 0x3e780, v90
	global_store_dwordx4 v[102:103], v[170:173], off
	s_cbranch_vccnz .LBB0_594
	v_mov_b32_e32 v91, v1
	v_lshl_add_u64 v[112:113], v[148:149], 0, v[90:91]
	v_add_u32_e32 v194, 0x90, v202
	v_lshlrev_b32_e32 v194, 7, v194
	v_and_b32_e32 v194, 0x3ff80, v194
	v_mov_b32_e32 v195, v1
	v_lshl_add_u64 v[194:195], v[148:149], 0, v[194:195]
	global_load_dwordx4 v[222:225], v[194:195], off offset:16
	global_load_dwordx4 v[226:229], v[194:195], off
	global_load_dwordx4 v[230:233], v[194:195], off offset:80
	global_load_dwordx4 v[234:237], v[194:195], off offset:64
	ds_bpermute_b32 v112, v168, v94
	ds_bpermute_b32 v113, v168, v95
	ds_bpermute_b32 v120, v168, v104
	ds_bpermute_b32 v121, v168, v105
	ds_bpermute_b32 v128, v168, v96
	ds_bpermute_b32 v132, v168, v92
	ds_bpermute_b32 v129, v168, v97
	ds_bpermute_b32 v133, v168, v93
	s_waitcnt vmcnt(4) lgkmcnt(0)
	v_mov_b32_e32 v170, v206
	v_mov_b32_e32 v171, v207
	v_mov_b32_e32 v172, v208
	v_mov_b32_e32 v173, v209
	v_mov_b32_e32 v174, v210
	v_mov_b32_e32 v175, v211
	v_mov_b32_e32 v176, v212
	v_mov_b32_e32 v177, v213
	v_mov_b32_e32 v178, v214
	v_mov_b32_e32 v179, v215
	v_mov_b32_e32 v180, v216
	v_mov_b32_e32 v181, v217
	v_mov_b32_e32 v182, v218
	v_mov_b32_e32 v183, v219
	v_mov_b32_e32 v184, v220
	v_mov_b32_e32 v185, v221
	v_pk_mul_f32 v[120:121], v[178:179], v[120:121]
	v_pk_mul_f32 v[112:113], v[182:183], v[112:113]
	v_pk_mul_f32 v[128:129], v[184:185], v[128:129]
	v_cndmask_b32_e64 v113, v113, -v113, s[46:47]
	v_cndmask_b32_e64 v112, v112, -v112, s[46:47]
	v_pk_fma_f32 v[94:95], v[94:95], v[174:175], v[112:113]
	v_pk_mul_f32 v[112:113], v[180:181], v[132:133]
	v_cndmask_b32_e64 v129, v129, -v129, s[46:47]
	v_cndmask_b32_e64 v128, v128, -v128, s[46:47]
	v_cndmask_b32_e64 v113, v113, -v113, s[46:47]
	v_cndmask_b32_e64 v112, v112, -v112, s[46:47]
	v_cndmask_b32_e64 v121, v121, -v121, s[46:47]
	v_cndmask_b32_e64 v120, v120, -v120, s[46:47]
	v_pk_fma_f32 v[96:97], v[96:97], v[176:177], v[128:129]
	v_pk_fma_f32 v[92:93], v[92:93], v[172:173], v[112:113]
	v_pk_fma_f32 v[104:105], v[104:105], v[170:171], v[120:121]
.LBB0_594:
	v_add_f32_e32 v91, v161, v163
	v_fmamk_f32 v91, v91, 0x3b2aaaab, v239
	v_mul_f32_e32 v99, 0x4b800000, v91
	v_cmp_gt_f32_e32 vcc, s55, v91
	v_cvt_pk_bf16_f32 v163, v92, v93
	v_mov_b64_e32 v[92:93], s[58:59]
	v_cndmask_b32_e32 v91, v91, v99, vcc
	v_rsq_f32_e32 v91, v91
	v_cvt_pk_bf16_f32 v160, v94, v95
	v_mad_i64_i32 v[92:93], s[6:7], v156, s4, v[92:93]
	v_mul_f32_e32 v94, 0x45800000, v91
	v_cvt_pk_bf16_f32 v161, v96, v97
	v_cndmask_b32_e32 v96, v91, v94, vcc
	v_lshl_add_u64 v[92:93], s[18:19], 1, v[92:93]
	v_lshl_add_u64 v[94:95], v[92:93], 0, v[0:1]
	v_add_u32_e32 v91, 0x90, v154
	v_mul_f32_e32 v92, 0x3e16c740, v96
	v_pk_mul_f32 v[96:97], v[82:83], v[92:93] op_sel_hi:[1,0]
	v_lshlrev_b32_e32 v82, 7, v91
	v_cvt_pk_bf16_f32 v162, v104, v105
	v_pk_mul_f32 v[88:89], v[88:89], v[92:93] op_sel_hi:[1,0]
	v_pk_mul_f32 v[86:87], v[86:87], v[92:93] op_sel_hi:[1,0]
	v_pk_mul_f32 v[84:85], v[84:85], v[92:93] op_sel_hi:[1,0]
	s_and_b64 vcc, exec, s[50:51]
	v_and_b32_e32 v82, 0x3ef80, v82
	global_store_dwordx4 v[94:95], v[160:163], off
	s_cbranch_vccnz .LBB0_596
	v_mov_b32_e32 v83, v1
	v_lshl_add_u64 v[104:105], v[148:149], 0, v[82:83]
	v_add_u32_e32 v194, 0xa0, v202
	v_lshlrev_b32_e32 v194, 7, v194
	v_and_b32_e32 v194, 0x3ff80, v194
	v_mov_b32_e32 v195, v1
	v_lshl_add_u64 v[194:195], v[148:149], 0, v[194:195]
	global_load_dwordx4 v[206:209], v[194:195], off offset:16
	global_load_dwordx4 v[210:213], v[194:195], off
	global_load_dwordx4 v[214:217], v[194:195], off offset:80
	global_load_dwordx4 v[218:221], v[194:195], off offset:64
	ds_bpermute_b32 v104, v168, v86
	ds_bpermute_b32 v105, v168, v87
	ds_bpermute_b32 v112, v168, v96
	ds_bpermute_b32 v113, v168, v97
	ds_bpermute_b32 v120, v168, v88
	ds_bpermute_b32 v128, v168, v84
	ds_bpermute_b32 v121, v168, v89
	ds_bpermute_b32 v129, v168, v85
	s_waitcnt vmcnt(4) lgkmcnt(0)
	v_mov_b32_e32 v160, v222
	v_mov_b32_e32 v161, v223
	v_mov_b32_e32 v162, v224
	v_mov_b32_e32 v163, v225
	v_mov_b32_e32 v170, v226
	v_mov_b32_e32 v171, v227
	v_mov_b32_e32 v172, v228
	v_mov_b32_e32 v173, v229
	v_mov_b32_e32 v174, v230
	v_mov_b32_e32 v175, v231
	v_mov_b32_e32 v176, v232
	v_mov_b32_e32 v177, v233
	v_mov_b32_e32 v178, v234
	v_mov_b32_e32 v179, v235
	v_mov_b32_e32 v180, v236
	v_mov_b32_e32 v181, v237
	v_pk_mul_f32 v[112:113], v[174:175], v[112:113]
	v_pk_mul_f32 v[104:105], v[178:179], v[104:105]
	v_pk_mul_f32 v[120:121], v[180:181], v[120:121]
	v_cndmask_b32_e64 v105, v105, -v105, s[46:47]
	v_cndmask_b32_e64 v104, v104, -v104, s[46:47]
	v_pk_fma_f32 v[86:87], v[86:87], v[170:171], v[104:105]
	v_pk_mul_f32 v[104:105], v[176:177], v[128:129]
	v_cndmask_b32_e64 v121, v121, -v121, s[46:47]
	v_cndmask_b32_e64 v120, v120, -v120, s[46:47]
	v_cndmask_b32_e64 v105, v105, -v105, s[46:47]
	v_cndmask_b32_e64 v104, v104, -v104, s[46:47]
	v_cndmask_b32_e64 v113, v113, -v113, s[46:47]
	v_cndmask_b32_e64 v112, v112, -v112, s[46:47]
	v_pk_fma_f32 v[88:89], v[88:89], v[172:173], v[120:121]
	v_pk_fma_f32 v[84:85], v[84:85], v[162:163], v[104:105]
	v_pk_fma_f32 v[96:97], v[96:97], v[160:161], v[112:113]
; __device__ __forceinline__ unsigned pk2(float lo, float hi) { f32x2_t v = {lo, hi}; bf16x2_t b = __builtin_convertvector(v, bf16x2_t); return __builtin_bit_cast(unsigned, b); }
; __device__ __forceinline__ float fast_sigmoid(float x) { return __builtin_amdgcn_rcpf(1.f + __expf(-x)); }
;     __device__ __forceinline__ void operator()(const f32x4 (&acc)[2][2][4][2], const Unit& u, int wr, int wc, int fr, int fq) const {
;     ...
;                     const int row = row0 + ai * HALF + m * 16; const float rs = rsv[ai][m] * scale;
;                     f32x4 v0 = acc[ai][bj][m][0] * rs, v1 = acc[ai][bj][m][1] * rs;
;                     if (rp) {
;                         const int pos = row & (SEQ - 1); const float* rb = rope + pos * 32 + 8 * (fq & 1); const bool hi2 = (fq >> 1) != 0;
;                         const f32x4 cs0 = *(const f32x4*)(rb), cs1 = *(const f32x4*)(rb + 4), sn0 = *(const f32x4*)(rb + 16), sn1 = *(const f32x4*)(rb + 20);
; #pragma unroll
;                         for (int e = 0; e < 4; ++e) { const float q0 = __shfl_xor(v0[e], 32), q1 = __shfl_xor(v1[e], 32);
;                             v0[e] = hi2 ? v0[e] * cs0[e] + q0 * sn0[e] : v0[e] * cs0[e] - q0 * sn0[e];
;                             v1[e] = hi2 ? v1[e] * cs1[e] + q1 * sn1[e] : v1[e] * cs1[e] - q1 * sn1[e]; } }
;                     if (sig) {
; #pragma unroll
;                         for (int e = 0; e < 4; ++e) { v0[e] = fast_sigmoid(v0[e]); v1[e] = fast_sigmoid(v1[e]); } }
;                     if (sq) { float s = (v0[0] * v0[0] + v0[1] * v0[1]) + (v0[2] * v0[2] + v0[3] * v0[3]) + (v1[0] * v1[0] + v1[1] * v1[1]) + (v1[2] * v1[2] + v1[3] * v1[3]);
;                         s += __shfl_xor(s, 16); s += __shfl_xor(s, 32); if (fq == 0) sq[(size_t)row * sqp] = s; }
;                     u32x4 w; w.x = pk2(v0[0], v0[1]); w.y = pk2(v0[2], v0[3]); w.z = pk2(v1[0], v1[1]); w.w = pk2(v1[2], v1[3]);
;                     *(u32x4*)(O + (size_t)row * ldc + c0 + 8 * fq) = w;
.LBB0_596:
	v_add_f32_e32 v83, v157, v159
	v_fmamk_f32 v83, v83, 0x3b2aaaab, v239
	v_mul_f32_e32 v93, 0x4b800000, v83
	v_cmp_gt_f32_e32 vcc, s55, v83
	v_cvt_pk_bf16_f32 v159, v84, v85
	v_mov_b64_e32 v[84:85], s[58:59]
	v_cndmask_b32_e32 v83, v83, v93, vcc
	v_rsq_f32_e32 v83, v83
	v_cvt_pk_bf16_f32 v156, v86, v87
	v_mad_i64_i32 v[84:85], s[6:7], v91, s4, v[84:85]
	v_mul_f32_e32 v86, 0x45800000, v83
	v_cvt_pk_bf16_f32 v157, v88, v89
	v_cndmask_b32_e32 v88, v83, v86, vcc
	v_lshl_add_u64 v[84:85], s[18:19], 1, v[84:85]
	v_lshl_add_u64 v[86:87], v[84:85], 0, v[0:1]
	v_add_u32_e32 v83, 0xa0, v154
	v_mul_f32_e32 v84, 0x3e16c740, v88
	v_pk_mul_f32 v[88:89], v[74:75], v[84:85] op_sel_hi:[1,0]
	v_lshlrev_b32_e32 v74, 7, v83
	v_cvt_pk_bf16_f32 v158, v96, v97
	v_pk_mul_f32 v[80:81], v[80:81], v[84:85] op_sel_hi:[1,0]
	v_pk_mul_f32 v[78:79], v[78:79], v[84:85] op_sel_hi:[1,0]
	v_pk_mul_f32 v[76:77], v[76:77], v[84:85] op_sel_hi:[1,0]
	s_and_b64 vcc, exec, s[50:51]
	v_and_b32_e32 v74, 0x3f780, v74
	global_store_dwordx4 v[86:87], v[156:159], off
	s_cbranch_vccnz .LBB0_598
	v_mov_b32_e32 v75, v1
	v_lshl_add_u64 v[96:97], v[148:149], 0, v[74:75]
	v_add_u32_e32 v194, 0xb0, v202
	v_lshlrev_b32_e32 v194, 7, v194
	v_and_b32_e32 v194, 0x3ff80, v194
	v_mov_b32_e32 v195, v1
	v_lshl_add_u64 v[194:195], v[148:149], 0, v[194:195]
	global_load_dwordx4 v[222:225], v[194:195], off offset:16
	global_load_dwordx4 v[226:229], v[194:195], off
	global_load_dwordx4 v[230:233], v[194:195], off offset:80
	global_load_dwordx4 v[234:237], v[194:195], off offset:64
	ds_bpermute_b32 v96, v168, v78
	ds_bpermute_b32 v97, v168, v79
	ds_bpermute_b32 v104, v168, v88
	ds_bpermute_b32 v105, v168, v89
	ds_bpermute_b32 v112, v168, v80
	ds_bpermute_b32 v120, v168, v76
	ds_bpermute_b32 v113, v168, v81
	ds_bpermute_b32 v121, v168, v77
	s_waitcnt vmcnt(4) lgkmcnt(0)
	v_mov_b32_e32 v156, v206
	v_mov_b32_e32 v157, v207
	v_mov_b32_e32 v158, v208
	v_mov_b32_e32 v159, v209
	v_mov_b32_e32 v160, v210
	v_mov_b32_e32 v161, v211
	v_mov_b32_e32 v162, v212
	v_mov_b32_e32 v163, v213
	v_mov_b32_e32 v170, v214
	v_mov_b32_e32 v171, v215
	v_mov_b32_e32 v172, v216
	v_mov_b32_e32 v173, v217
	v_mov_b32_e32 v174, v218
	v_mov_b32_e32 v175, v219
	v_mov_b32_e32 v176, v220
	v_mov_b32_e32 v177, v221
	v_pk_mul_f32 v[104:105], v[170:171], v[104:105]
	v_pk_mul_f32 v[96:97], v[174:175], v[96:97]
	v_pk_mul_f32 v[112:113], v[176:177], v[112:113]
	v_cndmask_b32_e64 v97, v97, -v97, s[46:47]
	v_cndmask_b32_e64 v96, v96, -v96, s[46:47]
	v_pk_fma_f32 v[78:79], v[78:79], v[160:161], v[96:97]
	v_pk_mul_f32 v[96:97], v[172:173], v[120:121]
	v_cndmask_b32_e64 v113, v113, -v113, s[46:47]
	v_cndmask_b32_e64 v112, v112, -v112, s[46:47]
	v_cndmask_b32_e64 v97, v97, -v97, s[46:47]
	v_cndmask_b32_e64 v96, v96, -v96, s[46:47]
	v_cndmask_b32_e64 v105, v105, -v105, s[46:47]
	v_cndmask_b32_e64 v104, v104, -v104, s[46:47]
	v_pk_fma_f32 v[80:81], v[80:81], v[162:163], v[112:113]
	v_pk_fma_f32 v[76:77], v[76:77], v[158:159], v[96:97]
	v_pk_fma_f32 v[88:89], v[88:89], v[156:157], v[104:105]
.LBB0_598:
	s_waitcnt lgkmcnt(0)
	v_add_f32_e32 v75, v131, v134
	v_fmamk_f32 v75, v75, 0x3b2aaaab, v239
	v_mul_f32_e32 v85, 0x4b800000, v75
	v_cmp_gt_f32_e32 vcc, s55, v75
	v_cvt_pk_bf16_f32 v135, v76, v77
	v_mov_b64_e32 v[76:77], s[58:59]
	v_cndmask_b32_e32 v75, v75, v85, vcc
	v_rsq_f32_e32 v75, v75
	v_cvt_pk_bf16_f32 v132, v78, v79
	v_mad_i64_i32 v[76:77], s[6:7], v83, s4, v[76:77]
	v_mul_f32_e32 v78, 0x45800000, v75
	v_cvt_pk_bf16_f32 v133, v80, v81
	v_cndmask_b32_e32 v80, v75, v78, vcc
	v_lshl_add_u64 v[76:77], s[18:19], 1, v[76:77]
	v_lshl_add_u64 v[78:79], v[76:77], 0, v[0:1]
	v_add_u32_e32 v75, 0xb0, v154
	v_mul_f32_e32 v76, 0x3e16c740, v80
	v_pk_mul_f32 v[80:81], v[66:67], v[76:77] op_sel_hi:[1,0]
	v_lshlrev_b32_e32 v66, 7, v75
	v_cvt_pk_bf16_f32 v134, v88, v89
	v_pk_mul_f32 v[72:73], v[72:73], v[76:77] op_sel_hi:[1,0]
	v_pk_mul_f32 v[70:71], v[70:71], v[76:77] op_sel_hi:[1,0]
	v_pk_mul_f32 v[68:69], v[68:69], v[76:77] op_sel_hi:[1,0]
	s_and_b64 vcc, exec, s[50:51]
	v_and_b32_e32 v66, 0x3ff80, v66
	global_store_dwordx4 v[78:79], v[132:135], off
	s_cbranch_vccnz .LBB0_600
	v_mov_b32_e32 v67, v1
	v_lshl_add_u64 v[88:89], v[148:149], 0, v[66:67]
	ds_bpermute_b32 v88, v168, v70
	ds_bpermute_b32 v89, v168, v71
	ds_bpermute_b32 v96, v168, v80
	ds_bpermute_b32 v97, v168, v81
	ds_bpermute_b32 v104, v168, v72
	ds_bpermute_b32 v112, v168, v68
	ds_bpermute_b32 v105, v168, v73
	ds_bpermute_b32 v113, v168, v69
	s_waitcnt vmcnt(0) lgkmcnt(0)
	v_mov_b32_e32 v132, v222
	v_mov_b32_e32 v133, v223
	v_mov_b32_e32 v134, v224
	v_mov_b32_e32 v135, v225
	v_mov_b32_e32 v154, v226
	v_mov_b32_e32 v155, v227
	v_mov_b32_e32 v156, v228
	v_mov_b32_e32 v157, v229
	v_mov_b32_e32 v158, v230
	v_mov_b32_e32 v159, v231
	v_mov_b32_e32 v160, v232
	v_mov_b32_e32 v161, v233
	v_mov_b32_e32 v162, v234
	v_mov_b32_e32 v163, v235
	v_mov_b32_e32 v164, v236
	v_mov_b32_e32 v165, v237
	v_pk_mul_f32 v[96:97], v[158:159], v[96:97]
	v_pk_mul_f32 v[88:89], v[162:163], v[88:89]
	v_pk_mul_f32 v[104:105], v[164:165], v[104:105]
	v_cndmask_b32_e64 v89, v89, -v89, s[46:47]
	v_cndmask_b32_e64 v88, v88, -v88, s[46:47]
	v_pk_fma_f32 v[70:71], v[70:71], v[154:155], v[88:89]
	v_pk_mul_f32 v[88:89], v[160:161], v[112:113]
	v_cndmask_b32_e64 v105, v105, -v105, s[46:47]
	v_cndmask_b32_e64 v104, v104, -v104, s[46:47]
	v_cndmask_b32_e64 v89, v89, -v89, s[46:47]
	v_cndmask_b32_e64 v88, v88, -v88, s[46:47]
	v_cndmask_b32_e64 v97, v97, -v97, s[46:47]
	v_cndmask_b32_e64 v96, v96, -v96, s[46:47]
	v_pk_fma_f32 v[72:73], v[72:73], v[156:157], v[104:105]
	v_pk_fma_f32 v[68:69], v[68:69], v[134:135], v[88:89]
	v_pk_fma_f32 v[80:81], v[80:81], v[132:133], v[96:97]
;     __device__ __forceinline__ void operator()(const f32x4 (&acc)[2][2][4][2], const Unit& u, int wr, int wc, int fr, int fq) const {
;     ...
;         for (int bj = 0; bj < 2; ++bj) {
;             const int c0 = u.pn * BM + bj * HALF + wc * 32;
;             float scale = 1.f; bool sig = false, rp = false, st = true; float* sq = nullptr; int sqp = 0;
;             if (mode == 1) { const int slab = c0 >> 7;
;                 if (slab < 3) { sq = ssq_q + 4 * slab + wc; sqp = 16; } else if (slab < 5) { sq = ssq_kv + 4 * (slab - 3) + wc; sqp = 8; } else if (slab == 5) { rp = (wc == 0); st = (wc == 0); }
;                 else if (slab < 14) scale = C2_64; else if (slab < 18) {} else if (slab < 26) scale = C2_64; else if (slab < 42) {} else sig = true;
;             } else if (mode == 2) { rp = ((c0 % 96) == 64); scale = C2_96; }
;             if (!st) continue;
; #pragma unroll
;             for (int ai = 0; ai < 2; ++ai)
; #pragma unroll
;                 for (int m = 0; m < 4; ++m) {
;                     const int row = row0 + ai * HALF + m * 16; const float rs = rsv[ai][m] * scale;
;                     f32x4 v0 = acc[ai][bj][m][0] * rs, v1 = acc[ai][bj][m][1] * rs;
;                     if (rp) {
;                         const int pos = row & (SEQ - 1); const float* rb = rope + pos * 32 + 8 * (fq & 1); const bool hi2 = (fq >> 1) != 0;
;                         const f32x4 cs0 = *(const f32x4*)(rb), cs1 = *(const f32x4*)(rb + 4), sn0 = *(const f32x4*)(rb + 16), sn1 = *(const f32x4*)(rb + 20);
; #pragma unroll
;                         for (int e = 0; e < 4; ++e) { const float q0 = __shfl_xor(v0[e], 32), q1 = __shfl_xor(v1[e], 32);
;                             v0[e] = hi2 ? v0[e] * cs0[e] + q0 * sn0[e] : v0[e] * cs0[e] - q0 * sn0[e];
;                             v1[e] = hi2 ? v1[e] * cs1[e] + q1 * sn1[e] : v1[e] * cs1[e] - q1 * sn1[e]; } }
;                     if (sig) {
; #pragma unroll
;                         for (int e = 0; e < 4; ++e) { v0[e] = fast_sigmoid(v0[e]); v1[e] = fast_sigmoid(v1[e]); } }
;                     if (sq) { float s = (v0[0] * v0[0] + v0[1] * v0[1]) + (v0[2] * v0[2] + v0[3] * v0[3]) + (v1[0] * v1[0] + v1[1] * v1[1]) + (v1[2] * v1[2] + v1[3] * v1[3]);
;                         s += __shfl_xor(s, 16); s += __shfl_xor(s, 32); if (fq == 0) sq[(size_t)row * sqp] = s; }
.LBB0_600:
	v_cvt_pk_bf16_f32 v70, v70, v71
	v_cvt_pk_bf16_f32 v71, v72, v73
	v_cvt_pk_bf16_f32 v73, v68, v69
	v_mov_b64_e32 v[68:69], s[58:59]
	v_mad_i64_i32 v[68:69], s[6:7], v75, s4, v[68:69]
	s_or_b32 s4, s18, 0x80
	s_mul_hi_i32 s6, s4, 0x2aaaaaab
	s_lshr_b32 s7, s6, 31
	s_lshr_b32 s6, s6, 4
	s_add_i32 s6, s6, s7
	v_lshl_add_u64 v[68:69], s[18:19], 1, v[68:69]
	s_mulk_i32 s6, 0x60
	v_cvt_pk_bf16_f32 v72, v80, v81
	v_lshl_add_u64 v[68:69], v[68:69], 0, v[0:1]
	s_sub_i32 s4, s4, s6
	v_mov_b32_e32 v131, v130
	global_store_dwordx4 v[68:69], v[70:73], off
	s_cmp_eq_u32 s4, 64
	s_cselect_b64 s[18:19], -1, 0
	v_mov_b32_e32 v70, v130
	v_mov_b32_e32 v71, v130
	s_cmp_lg_u32 s4, 64
	v_pk_mul_f32 v[64:65], v[64:65], v[70:71]
	v_pk_mul_f32 v[62:63], v[62:63], v[130:131]
	v_pk_mul_f32 v[60:61], v[60:61], v[70:71]
	v_pk_mul_f32 v[58:59], v[58:59], v[130:131]
	s_cbranch_scc1 .LBB0_602
	v_mov_b32_e32 v123, v1
	v_lshl_add_u64 v[80:81], v[148:149], 0, v[122:123]
	global_load_dwordx4 v[70:73], v[80:81], off offset:16
	global_load_dwordx4 v[120:123], v[80:81], off
	global_load_dwordx4 v[128:131], v[80:81], off offset:80
	global_load_dwordx4 v[132:135], v[80:81], off offset:64
	v_add_u32_e32 v194, 0x10, v202
	v_lshlrev_b32_e32 v194, 7, v194
	v_and_b32_e32 v194, 0x3ff80, v194
	v_mov_b32_e32 v195, v1
	v_lshl_add_u64 v[194:195], v[148:149], 0, v[194:195]
	global_load_dwordx4 v[222:225], v[194:195], off offset:16
	global_load_dwordx4 v[226:229], v[194:195], off
	global_load_dwordx4 v[230:233], v[194:195], off offset:80
	global_load_dwordx4 v[234:237], v[194:195], off offset:64
	ds_bpermute_b32 v80, v168, v62
	ds_bpermute_b32 v81, v168, v63
	ds_bpermute_b32 v88, v168, v58
	ds_bpermute_b32 v89, v168, v59
	ds_bpermute_b32 v96, v168, v64
	ds_bpermute_b32 v104, v168, v60
	ds_bpermute_b32 v97, v168, v65
	ds_bpermute_b32 v105, v168, v61
	s_waitcnt vmcnt(4) lgkmcnt(0)
	v_pk_mul_f32 v[88:89], v[128:129], v[88:89]
	v_pk_mul_f32 v[80:81], v[132:133], v[80:81]
	v_pk_mul_f32 v[96:97], v[134:135], v[96:97]
	v_cndmask_b32_e64 v81, v81, -v81, s[46:47]
	v_cndmask_b32_e64 v80, v80, -v80, s[46:47]
	v_pk_fma_f32 v[62:63], v[62:63], v[120:121], v[80:81]
	v_pk_mul_f32 v[80:81], v[130:131], v[104:105]
	v_cndmask_b32_e64 v97, v97, -v97, s[46:47]
	v_cndmask_b32_e64 v96, v96, -v96, s[46:47]
	v_cndmask_b32_e64 v81, v81, -v81, s[46:47]
	v_cndmask_b32_e64 v80, v80, -v80, s[46:47]
	v_cndmask_b32_e64 v89, v89, -v89, s[46:47]
	v_cndmask_b32_e64 v88, v88, -v88, s[46:47]
	v_pk_fma_f32 v[64:65], v[64:65], v[122:123], v[96:97]
	v_pk_fma_f32 v[60:61], v[60:61], v[72:73], v[80:81]
	v_pk_fma_f32 v[58:59], v[58:59], v[70:71], v[88:89]
.LBB0_602:
	v_mov_b32_e32 v125, v124
	v_cvt_pk_bf16_f32 v62, v62, v63
	v_cvt_pk_bf16_f32 v63, v64, v65
	v_cvt_pk_bf16_f32 v64, v58, v59
	v_mov_b32_e32 v58, v124
	v_mov_b32_e32 v59, v124
	v_cndmask_b32_e64 v0, 0, 1, s[18:19]
	v_cvt_pk_bf16_f32 v65, v60, v61
	v_pk_mul_f32 v[56:57], v[56:57], v[58:59]
	v_pk_mul_f32 v[54:55], v[54:55], v[124:125]
	v_pk_mul_f32 v[52:53], v[52:53], v[58:59]
	v_cmp_ne_u32_e64 s[50:51], 1, v0
	s_andn2_b64 vcc, exec, s[18:19]
	v_pk_mul_f32 v[50:51], v[50:51], v[124:125]
	global_store_dwordx4 v[126:127], v[62:65], off offset:256
	s_cbranch_vccnz .LBB0_604
	v_mov_b32_e32 v115, v1
	v_lshl_add_u64 v[80:81], v[148:149], 0, v[114:115]
	v_add_u32_e32 v194, 0x20, v202
	v_lshlrev_b32_e32 v194, 7, v194
	v_and_b32_e32 v194, 0x3ff80, v194
	v_mov_b32_e32 v195, v1
	v_lshl_add_u64 v[194:195], v[148:149], 0, v[194:195]
	global_load_dwordx4 v[206:209], v[194:195], off offset:16
	global_load_dwordx4 v[210:213], v[194:195], off
	global_load_dwordx4 v[214:217], v[194:195], off offset:80
	global_load_dwordx4 v[218:221], v[194:195], off offset:64
	ds_bpermute_b32 v88, v168, v50
	ds_bpermute_b32 v89, v168, v51
	ds_bpermute_b32 v80, v168, v54
	ds_bpermute_b32 v81, v168, v55
	ds_bpermute_b32 v96, v168, v52
	ds_bpermute_b32 v97, v168, v53
	s_waitcnt vmcnt(4) lgkmcnt(0)
	v_mov_b32_e32 v58, v222
	v_mov_b32_e32 v59, v223
	v_mov_b32_e32 v60, v224
	v_mov_b32_e32 v61, v225
	v_mov_b32_e32 v62, v226
	v_mov_b32_e32 v63, v227
	v_mov_b32_e32 v64, v228
	v_mov_b32_e32 v65, v229
	v_mov_b32_e32 v70, v230
	v_mov_b32_e32 v71, v231
	v_mov_b32_e32 v72, v232
	v_mov_b32_e32 v73, v233
	v_mov_b32_e32 v112, v234
	v_mov_b32_e32 v113, v235
	v_mov_b32_e32 v114, v236
	v_mov_b32_e32 v115, v237
	v_pk_mul_f32 v[70:71], v[70:71], v[88:89]
	ds_bpermute_b32 v88, v168, v56
	ds_bpermute_b32 v89, v168, v57
	v_pk_mul_f32 v[80:81], v[112:113], v[80:81]
	s_waitcnt lgkmcnt(0)
	v_pk_mul_f32 v[88:89], v[114:115], v[88:89]
	v_cndmask_b32_e64 v81, v81, -v81, s[46:47]
	v_cndmask_b32_e64 v80, v80, -v80, s[46:47]
	v_cndmask_b32_e64 v89, v89, -v89, s[46:47]
	v_cndmask_b32_e64 v88, v88, -v88, s[46:47]
	v_pk_fma_f32 v[54:55], v[54:55], v[62:63], v[80:81]
	v_pk_mul_f32 v[62:63], v[72:73], v[96:97]
	v_pk_fma_f32 v[56:57], v[56:57], v[64:65], v[88:89]
	v_cndmask_b32_e64 v63, v63, -v63, s[46:47]
	v_cndmask_b32_e64 v62, v62, -v62, s[46:47]
	v_cndmask_b32_e64 v65, v71, -v71, s[46:47]
	v_cndmask_b32_e64 v64, v70, -v70, s[46:47]
	v_pk_fma_f32 v[52:53], v[52:53], v[60:61], v[62:63]
	v_pk_fma_f32 v[50:51], v[50:51], v[58:59], v[64:65]
; __device__ __forceinline__ unsigned pk2(float lo, float hi) { f32x2_t v = {lo, hi}; bf16x2_t b = __builtin_convertvector(v, bf16x2_t); return __builtin_bit_cast(unsigned, b); }
; __device__ __forceinline__ float fast_sigmoid(float x) { return __builtin_amdgcn_rcpf(1.f + __expf(-x)); }
;     __device__ __forceinline__ void operator()(const f32x4 (&acc)[2][2][4][2], const Unit& u, int wr, int wc, int fr, int fq) const {
;     ...
;                     const int row = row0 + ai * HALF + m * 16; const float rs = rsv[ai][m] * scale;
;                     f32x4 v0 = acc[ai][bj][m][0] * rs, v1 = acc[ai][bj][m][1] * rs;
;                     if (rp) {
;                         const int pos = row & (SEQ - 1); const float* rb = rope + pos * 32 + 8 * (fq & 1); const bool hi2 = (fq >> 1) != 0;
;                         const f32x4 cs0 = *(const f32x4*)(rb), cs1 = *(const f32x4*)(rb + 4), sn0 = *(const f32x4*)(rb + 16), sn1 = *(const f32x4*)(rb + 20);
; #pragma unroll
;                         for (int e = 0; e < 4; ++e) { const float q0 = __shfl_xor(v0[e], 32), q1 = __shfl_xor(v1[e], 32);
;                             v0[e] = hi2 ? v0[e] * cs0[e] + q0 * sn0[e] : v0[e] * cs0[e] - q0 * sn0[e];
;                             v1[e] = hi2 ? v1[e] * cs1[e] + q1 * sn1[e] : v1[e] * cs1[e] - q1 * sn1[e]; } }
;                     if (sig) {
; #pragma unroll
;                         for (int e = 0; e < 4; ++e) { v0[e] = fast_sigmoid(v0[e]); v1[e] = fast_sigmoid(v1[e]); } }
;                     if (sq) { float s = (v0[0] * v0[0] + v0[1] * v0[1]) + (v0[2] * v0[2] + v0[3] * v0[3]) + (v1[0] * v1[0] + v1[1] * v1[1]) + (v1[2] * v1[2] + v1[3] * v1[3]);
;                         s += __shfl_xor(s, 16); s += __shfl_xor(s, 32); if (fq == 0) sq[(size_t)row * sqp] = s; }
;                     u32x4 w; w.x = pk2(v0[0], v0[1]); w.y = pk2(v0[2], v0[3]); w.z = pk2(v1[0], v1[1]); w.w = pk2(v1[2], v1[3]);
;                     *(u32x4*)(O + (size_t)row * ldc + c0 + 8 * fq) = w;
.LBB0_604:
	v_mov_b32_e32 v117, v116
	v_cvt_pk_bf16_f32 v54, v54, v55
	v_cvt_pk_bf16_f32 v55, v56, v57
	v_cvt_pk_bf16_f32 v56, v50, v51
	v_mov_b32_e32 v50, v116
	v_mov_b32_e32 v51, v116
	v_cvt_pk_bf16_f32 v57, v52, v53
	v_pk_mul_f32 v[48:49], v[48:49], v[50:51]
	v_pk_mul_f32 v[46:47], v[46:47], v[116:117]
	v_pk_mul_f32 v[44:45], v[44:45], v[50:51]
	s_and_b64 vcc, exec, s[50:51]
	v_pk_mul_f32 v[42:43], v[42:43], v[116:117]
	global_store_dwordx4 v[118:119], v[54:57], off offset:256
	s_cbranch_vccnz .LBB0_606
	v_mov_b32_e32 v107, v1
	v_lshl_add_u64 v[62:63], v[148:149], 0, v[106:107]
	s_nop 0
	v_add_u32_e32 v194, 0x30, v202
	v_lshlrev_b32_e32 v194, 7, v194
	v_and_b32_e32 v194, 0x3ff80, v194
	v_mov_b32_e32 v195, v1
	v_lshl_add_u64 v[194:195], v[148:149], 0, v[194:195]
	global_load_dwordx4 v[222:225], v[194:195], off offset:16
	global_load_dwordx4 v[226:229], v[194:195], off
	global_load_dwordx4 v[230:233], v[194:195], off offset:80
	global_load_dwordx4 v[234:237], v[194:195], off offset:64
	ds_bpermute_b32 v70, v168, v46
	ds_bpermute_b32 v71, v168, v47
	ds_bpermute_b32 v72, v168, v42
	ds_bpermute_b32 v73, v168, v43
	s_waitcnt vmcnt(4) lgkmcnt(0)
	v_mov_b32_e32 v50, v206
	v_mov_b32_e32 v51, v207
	v_mov_b32_e32 v52, v208
	v_mov_b32_e32 v53, v209
	v_mov_b32_e32 v54, v210
	v_mov_b32_e32 v55, v211
	v_mov_b32_e32 v56, v212
	v_mov_b32_e32 v57, v213
	v_mov_b32_e32 v58, v214
	v_mov_b32_e32 v59, v215
	v_mov_b32_e32 v60, v216
	v_mov_b32_e32 v61, v217
	v_mov_b32_e32 v62, v218
	v_mov_b32_e32 v63, v219
	v_mov_b32_e32 v64, v220
	v_mov_b32_e32 v65, v221
	v_pk_mul_f32 v[58:59], v[58:59], v[72:73]
	v_pk_mul_f32 v[62:63], v[62:63], v[70:71]
	ds_bpermute_b32 v70, v168, v48
	ds_bpermute_b32 v71, v168, v49
	ds_bpermute_b32 v72, v168, v44
	ds_bpermute_b32 v73, v168, v45
	v_cndmask_b32_e64 v63, v63, -v63, s[46:47]
	v_cndmask_b32_e64 v62, v62, -v62, s[46:47]
	s_waitcnt lgkmcnt(2)
	v_pk_mul_f32 v[64:65], v[64:65], v[70:71]
	v_pk_fma_f32 v[46:47], v[46:47], v[54:55], v[62:63]
	v_cndmask_b32_e64 v65, v65, -v65, s[46:47]
	v_cndmask_b32_e64 v64, v64, -v64, s[46:47]
	s_waitcnt lgkmcnt(0)
	v_pk_mul_f32 v[54:55], v[60:61], v[72:73]
	v_pk_fma_f32 v[48:49], v[48:49], v[56:57], v[64:65]
	v_cndmask_b32_e64 v55, v55, -v55, s[46:47]
	v_cndmask_b32_e64 v54, v54, -v54, s[46:47]
	v_cndmask_b32_e64 v57, v59, -v59, s[46:47]
	v_cndmask_b32_e64 v56, v58, -v58, s[46:47]
	v_pk_fma_f32 v[44:45], v[44:45], v[52:53], v[54:55]
	v_pk_fma_f32 v[42:43], v[42:43], v[50:51], v[56:57]
.LBB0_606:
	v_mov_b32_e32 v109, v108
	v_cvt_pk_bf16_f32 v46, v46, v47
	v_cvt_pk_bf16_f32 v47, v48, v49
	v_cvt_pk_bf16_f32 v48, v42, v43
	v_mov_b32_e32 v42, v108
	v_mov_b32_e32 v43, v108
	v_cvt_pk_bf16_f32 v49, v44, v45
	v_pk_mul_f32 v[40:41], v[40:41], v[42:43]
	v_pk_mul_f32 v[38:39], v[38:39], v[108:109]
	v_pk_mul_f32 v[36:37], v[36:37], v[42:43]
	s_and_b64 vcc, exec, s[50:51]
	v_pk_mul_f32 v[34:35], v[34:35], v[108:109]
	global_store_dwordx4 v[110:111], v[46:49], off offset:256
	s_cbranch_vccnz .LBB0_608
	v_mov_b32_e32 v99, v1
	v_lshl_add_u64 v[54:55], v[148:149], 0, v[98:99]
	s_nop 0
	v_add_u32_e32 v194, 0x80, v202
	v_lshlrev_b32_e32 v194, 7, v194
	v_and_b32_e32 v194, 0x3ff80, v194
	v_mov_b32_e32 v195, v1
	v_lshl_add_u64 v[194:195], v[148:149], 0, v[194:195]
	global_load_dwordx4 v[206:209], v[194:195], off offset:16
	global_load_dwordx4 v[210:213], v[194:195], off
	global_load_dwordx4 v[214:217], v[194:195], off offset:80
	global_load_dwordx4 v[218:221], v[194:195], off offset:64
	ds_bpermute_b32 v58, v168, v38
	ds_bpermute_b32 v59, v168, v39
	ds_bpermute_b32 v60, v168, v34
	ds_bpermute_b32 v61, v168, v35
	s_waitcnt vmcnt(4) lgkmcnt(0)
	v_mov_b32_e32 v42, v222
	v_mov_b32_e32 v43, v223
	v_mov_b32_e32 v44, v224
	v_mov_b32_e32 v45, v225
	v_mov_b32_e32 v46, v226
	v_mov_b32_e32 v47, v227
	v_mov_b32_e32 v48, v228
	v_mov_b32_e32 v49, v229
	v_mov_b32_e32 v50, v230
	v_mov_b32_e32 v51, v231
	v_mov_b32_e32 v52, v232
	v_mov_b32_e32 v53, v233
	v_mov_b32_e32 v54, v234
	v_mov_b32_e32 v55, v235
	v_mov_b32_e32 v56, v236
	v_mov_b32_e32 v57, v237
	v_pk_mul_f32 v[50:51], v[50:51], v[60:61]
	v_pk_mul_f32 v[54:55], v[54:55], v[58:59]
	ds_bpermute_b32 v58, v168, v40
	ds_bpermute_b32 v59, v168, v41
	ds_bpermute_b32 v60, v168, v36
	ds_bpermute_b32 v61, v168, v37
	v_cndmask_b32_e64 v55, v55, -v55, s[46:47]
	v_cndmask_b32_e64 v54, v54, -v54, s[46:47]
	s_waitcnt lgkmcnt(2)
	v_pk_mul_f32 v[56:57], v[56:57], v[58:59]
	v_pk_fma_f32 v[38:39], v[38:39], v[46:47], v[54:55]
	v_cndmask_b32_e64 v57, v57, -v57, s[46:47]
	v_cndmask_b32_e64 v56, v56, -v56, s[46:47]
	s_waitcnt lgkmcnt(0)
	v_pk_mul_f32 v[46:47], v[52:53], v[60:61]
	v_pk_fma_f32 v[40:41], v[40:41], v[48:49], v[56:57]
	v_cndmask_b32_e64 v47, v47, -v47, s[46:47]
	v_cndmask_b32_e64 v46, v46, -v46, s[46:47]
	v_cndmask_b32_e64 v49, v51, -v51, s[46:47]
	v_cndmask_b32_e64 v48, v50, -v50, s[46:47]
	v_pk_fma_f32 v[36:37], v[36:37], v[44:45], v[46:47]
	v_pk_fma_f32 v[34:35], v[34:35], v[42:43], v[48:49]
; __device__ __forceinline__ unsigned pk2(float lo, float hi) { f32x2_t v = {lo, hi}; bf16x2_t b = __builtin_convertvector(v, bf16x2_t); return __builtin_bit_cast(unsigned, b); }
; __device__ __forceinline__ float fast_sigmoid(float x) { return __builtin_amdgcn_rcpf(1.f + __expf(-x)); }
;     __device__ __forceinline__ void operator()(const f32x4 (&acc)[2][2][4][2], const Unit& u, int wr, int wc, int fr, int fq) const {
;     ...
;                     const int row = row0 + ai * HALF + m * 16; const float rs = rsv[ai][m] * scale;
;                     f32x4 v0 = acc[ai][bj][m][0] * rs, v1 = acc[ai][bj][m][1] * rs;
;                     if (rp) {
;                         const int pos = row & (SEQ - 1); const float* rb = rope + pos * 32 + 8 * (fq & 1); const bool hi2 = (fq >> 1) != 0;
;                         const f32x4 cs0 = *(const f32x4*)(rb), cs1 = *(const f32x4*)(rb + 4), sn0 = *(const f32x4*)(rb + 16), sn1 = *(const f32x4*)(rb + 20);
; #pragma unroll
;                         for (int e = 0; e < 4; ++e) { const float q0 = __shfl_xor(v0[e], 32), q1 = __shfl_xor(v1[e], 32);
;                             v0[e] = hi2 ? v0[e] * cs0[e] + q0 * sn0[e] : v0[e] * cs0[e] - q0 * sn0[e];
;                             v1[e] = hi2 ? v1[e] * cs1[e] + q1 * sn1[e] : v1[e] * cs1[e] - q1 * sn1[e]; } }
;                     if (sig) {
; #pragma unroll
;                         for (int e = 0; e < 4; ++e) { v0[e] = fast_sigmoid(v0[e]); v1[e] = fast_sigmoid(v1[e]); } }
;                     if (sq) { float s = (v0[0] * v0[0] + v0[1] * v0[1]) + (v0[2] * v0[2] + v0[3] * v0[3]) + (v1[0] * v1[0] + v1[1] * v1[1]) + (v1[2] * v1[2] + v1[3] * v1[3]);
;                         s += __shfl_xor(s, 16); s += __shfl_xor(s, 32); if (fq == 0) sq[(size_t)row * sqp] = s; }
;                     u32x4 w; w.x = pk2(v0[0], v0[1]); w.y = pk2(v0[2], v0[3]); w.z = pk2(v1[0], v1[1]); w.w = pk2(v1[2], v1[3]);
;                     *(u32x4*)(O + (size_t)row * ldc + c0 + 8 * fq) = w;
.LBB0_608:
	v_mov_b32_e32 v101, v100
	v_cvt_pk_bf16_f32 v38, v38, v39
	v_cvt_pk_bf16_f32 v39, v40, v41
	v_cvt_pk_bf16_f32 v40, v34, v35
	v_mov_b32_e32 v34, v100
	v_mov_b32_e32 v35, v100
	v_cvt_pk_bf16_f32 v41, v36, v37
	v_pk_mul_f32 v[32:33], v[32:33], v[34:35]
	v_pk_mul_f32 v[30:31], v[30:31], v[100:101]
	v_pk_mul_f32 v[28:29], v[28:29], v[34:35]
	s_and_b64 vcc, exec, s[50:51]
	v_pk_mul_f32 v[26:27], v[26:27], v[100:101]
	global_store_dwordx4 v[102:103], v[38:41], off offset:256
	s_cbranch_vccnz .LBB0_610
	v_mov_b32_e32 v91, v1
	v_lshl_add_u64 v[46:47], v[148:149], 0, v[90:91]
	s_nop 0
	v_add_u32_e32 v194, 0x90, v202
	v_lshlrev_b32_e32 v194, 7, v194
	v_and_b32_e32 v194, 0x3ff80, v194
	v_mov_b32_e32 v195, v1
	v_lshl_add_u64 v[194:195], v[148:149], 0, v[194:195]
	global_load_dwordx4 v[222:225], v[194:195], off offset:16
	global_load_dwordx4 v[226:229], v[194:195], off
	global_load_dwordx4 v[230:233], v[194:195], off offset:80
	global_load_dwordx4 v[234:237], v[194:195], off offset:64
	ds_bpermute_b32 v50, v168, v30
	ds_bpermute_b32 v51, v168, v31
	ds_bpermute_b32 v52, v168, v26
	ds_bpermute_b32 v53, v168, v27
	s_waitcnt vmcnt(4) lgkmcnt(0)
	v_mov_b32_e32 v34, v206
	v_mov_b32_e32 v35, v207
	v_mov_b32_e32 v36, v208
	v_mov_b32_e32 v37, v209
	v_mov_b32_e32 v38, v210
	v_mov_b32_e32 v39, v211
	v_mov_b32_e32 v40, v212
	v_mov_b32_e32 v41, v213
	v_mov_b32_e32 v42, v214
	v_mov_b32_e32 v43, v215
	v_mov_b32_e32 v44, v216
	v_mov_b32_e32 v45, v217
	v_mov_b32_e32 v46, v218
	v_mov_b32_e32 v47, v219
	v_mov_b32_e32 v48, v220
	v_mov_b32_e32 v49, v221
	v_pk_mul_f32 v[42:43], v[42:43], v[52:53]
	v_pk_mul_f32 v[46:47], v[46:47], v[50:51]
	ds_bpermute_b32 v50, v168, v32
	ds_bpermute_b32 v51, v168, v33
	ds_bpermute_b32 v52, v168, v28
	ds_bpermute_b32 v53, v168, v29
	v_cndmask_b32_e64 v47, v47, -v47, s[46:47]
	v_cndmask_b32_e64 v46, v46, -v46, s[46:47]
	s_waitcnt lgkmcnt(2)
	v_pk_mul_f32 v[48:49], v[48:49], v[50:51]
	v_pk_fma_f32 v[30:31], v[30:31], v[38:39], v[46:47]
	v_cndmask_b32_e64 v49, v49, -v49, s[46:47]
	v_cndmask_b32_e64 v48, v48, -v48, s[46:47]
	s_waitcnt lgkmcnt(0)
	v_pk_mul_f32 v[38:39], v[44:45], v[52:53]
	v_pk_fma_f32 v[32:33], v[32:33], v[40:41], v[48:49]
	v_cndmask_b32_e64 v39, v39, -v39, s[46:47]
	v_cndmask_b32_e64 v38, v38, -v38, s[46:47]
	v_cndmask_b32_e64 v41, v43, -v43, s[46:47]
	v_cndmask_b32_e64 v40, v42, -v42, s[46:47]
	v_pk_fma_f32 v[28:29], v[28:29], v[36:37], v[38:39]
	v_pk_fma_f32 v[26:27], v[26:27], v[34:35], v[40:41]
.LBB0_610:
	v_mov_b32_e32 v93, v92
	v_cvt_pk_bf16_f32 v30, v30, v31
	v_cvt_pk_bf16_f32 v31, v32, v33
	v_cvt_pk_bf16_f32 v32, v26, v27
	v_mov_b32_e32 v26, v92
	v_mov_b32_e32 v27, v92
	v_cvt_pk_bf16_f32 v33, v28, v29
	v_pk_mul_f32 v[24:25], v[24:25], v[26:27]
	v_pk_mul_f32 v[22:23], v[22:23], v[92:93]
	v_pk_mul_f32 v[20:21], v[20:21], v[26:27]
	s_and_b64 vcc, exec, s[50:51]
	v_pk_mul_f32 v[18:19], v[18:19], v[92:93]
	global_store_dwordx4 v[94:95], v[30:33], off offset:256
	s_cbranch_vccnz .LBB0_612
	v_mov_b32_e32 v83, v1
	v_lshl_add_u64 v[38:39], v[148:149], 0, v[82:83]
	s_nop 0
	v_add_u32_e32 v194, 0xa0, v202
	v_lshlrev_b32_e32 v194, 7, v194
	v_and_b32_e32 v194, 0x3ff80, v194
	v_mov_b32_e32 v195, v1
	v_lshl_add_u64 v[194:195], v[148:149], 0, v[194:195]
	global_load_dwordx4 v[206:209], v[194:195], off offset:16
	global_load_dwordx4 v[210:213], v[194:195], off
	global_load_dwordx4 v[214:217], v[194:195], off offset:80
	global_load_dwordx4 v[218:221], v[194:195], off offset:64
	ds_bpermute_b32 v42, v168, v22
	ds_bpermute_b32 v43, v168, v23
	ds_bpermute_b32 v44, v168, v18
	ds_bpermute_b32 v45, v168, v19
	s_waitcnt vmcnt(4) lgkmcnt(0)
	v_mov_b32_e32 v26, v222
	v_mov_b32_e32 v27, v223
	v_mov_b32_e32 v28, v224
	v_mov_b32_e32 v29, v225
	v_mov_b32_e32 v30, v226
	v_mov_b32_e32 v31, v227
	v_mov_b32_e32 v32, v228
	v_mov_b32_e32 v33, v229
	v_mov_b32_e32 v34, v230
	v_mov_b32_e32 v35, v231
	v_mov_b32_e32 v36, v232
	v_mov_b32_e32 v37, v233
	v_mov_b32_e32 v38, v234
	v_mov_b32_e32 v39, v235
	v_mov_b32_e32 v40, v236
	v_mov_b32_e32 v41, v237
	v_pk_mul_f32 v[34:35], v[34:35], v[44:45]
	v_pk_mul_f32 v[38:39], v[38:39], v[42:43]
	ds_bpermute_b32 v42, v168, v24
	ds_bpermute_b32 v43, v168, v25
	ds_bpermute_b32 v44, v168, v20
	ds_bpermute_b32 v45, v168, v21
	v_cndmask_b32_e64 v39, v39, -v39, s[46:47]
	v_cndmask_b32_e64 v38, v38, -v38, s[46:47]
	s_waitcnt lgkmcnt(2)
	v_pk_mul_f32 v[40:41], v[40:41], v[42:43]
	v_pk_fma_f32 v[22:23], v[22:23], v[30:31], v[38:39]
	v_cndmask_b32_e64 v41, v41, -v41, s[46:47]
	v_cndmask_b32_e64 v40, v40, -v40, s[46:47]
	s_waitcnt lgkmcnt(0)
	v_pk_mul_f32 v[30:31], v[36:37], v[44:45]
	v_pk_fma_f32 v[24:25], v[24:25], v[32:33], v[40:41]
	v_cndmask_b32_e64 v31, v31, -v31, s[46:47]
	v_cndmask_b32_e64 v30, v30, -v30, s[46:47]
	v_cndmask_b32_e64 v33, v35, -v35, s[46:47]
	v_cndmask_b32_e64 v32, v34, -v34, s[46:47]
	v_pk_fma_f32 v[20:21], v[20:21], v[28:29], v[30:31]
	v_pk_fma_f32 v[18:19], v[18:19], v[26:27], v[32:33]
; __device__ __forceinline__ unsigned pk2(float lo, float hi) { f32x2_t v = {lo, hi}; bf16x2_t b = __builtin_convertvector(v, bf16x2_t); return __builtin_bit_cast(unsigned, b); }
; __device__ __forceinline__ float fast_sigmoid(float x) { return __builtin_amdgcn_rcpf(1.f + __expf(-x)); }
;     __device__ __forceinline__ void operator()(const f32x4 (&acc)[2][2][4][2], const Unit& u, int wr, int wc, int fr, int fq) const {
;     ...
;                     const int row = row0 + ai * HALF + m * 16; const float rs = rsv[ai][m] * scale;
;                     f32x4 v0 = acc[ai][bj][m][0] * rs, v1 = acc[ai][bj][m][1] * rs;
;                     if (rp) {
;                         const int pos = row & (SEQ - 1); const float* rb = rope + pos * 32 + 8 * (fq & 1); const bool hi2 = (fq >> 1) != 0;
;                         const f32x4 cs0 = *(const f32x4*)(rb), cs1 = *(const f32x4*)(rb + 4), sn0 = *(const f32x4*)(rb + 16), sn1 = *(const f32x4*)(rb + 20);
; #pragma unroll
;                         for (int e = 0; e < 4; ++e) { const float q0 = __shfl_xor(v0[e], 32), q1 = __shfl_xor(v1[e], 32);
;                             v0[e] = hi2 ? v0[e] * cs0[e] + q0 * sn0[e] : v0[e] * cs0[e] - q0 * sn0[e];
;                             v1[e] = hi2 ? v1[e] * cs1[e] + q1 * sn1[e] : v1[e] * cs1[e] - q1 * sn1[e]; } }
;                     if (sig) {
; #pragma unroll
;                         for (int e = 0; e < 4; ++e) { v0[e] = fast_sigmoid(v0[e]); v1[e] = fast_sigmoid(v1[e]); } }
;                     if (sq) { float s = (v0[0] * v0[0] + v0[1] * v0[1]) + (v0[2] * v0[2] + v0[3] * v0[3]) + (v1[0] * v1[0] + v1[1] * v1[1]) + (v1[2] * v1[2] + v1[3] * v1[3]);
;                         s += __shfl_xor(s, 16); s += __shfl_xor(s, 32); if (fq == 0) sq[(size_t)row * sqp] = s; }
;                     u32x4 w; w.x = pk2(v0[0], v0[1]); w.y = pk2(v0[2], v0[3]); w.z = pk2(v1[0], v1[1]); w.w = pk2(v1[2], v1[3]);
;                     *(u32x4*)(O + (size_t)row * ldc + c0 + 8 * fq) = w;
.LBB0_612:
	v_mov_b32_e32 v85, v84
	v_cvt_pk_bf16_f32 v22, v22, v23
	v_cvt_pk_bf16_f32 v23, v24, v25
	v_cvt_pk_bf16_f32 v24, v18, v19
	v_mov_b32_e32 v18, v84
	v_mov_b32_e32 v19, v84
	v_cvt_pk_bf16_f32 v25, v20, v21
	v_pk_mul_f32 v[16:17], v[16:17], v[18:19]
	v_pk_mul_f32 v[14:15], v[14:15], v[84:85]
	v_pk_mul_f32 v[12:13], v[12:13], v[18:19]
	s_and_b64 vcc, exec, s[50:51]
	v_pk_mul_f32 v[10:11], v[10:11], v[84:85]
	global_store_dwordx4 v[86:87], v[22:25], off offset:256
	s_cbranch_vccnz .LBB0_614
	v_mov_b32_e32 v75, v1
	v_lshl_add_u64 v[30:31], v[148:149], 0, v[74:75]
	s_nop 0
	v_add_u32_e32 v194, 0xb0, v202
	v_lshlrev_b32_e32 v194, 7, v194
	v_and_b32_e32 v194, 0x3ff80, v194
	v_mov_b32_e32 v195, v1
	v_lshl_add_u64 v[194:195], v[148:149], 0, v[194:195]
	global_load_dwordx4 v[222:225], v[194:195], off offset:16
	global_load_dwordx4 v[226:229], v[194:195], off
	global_load_dwordx4 v[230:233], v[194:195], off offset:80
	global_load_dwordx4 v[234:237], v[194:195], off offset:64
	ds_bpermute_b32 v34, v168, v14
	ds_bpermute_b32 v35, v168, v15
	ds_bpermute_b32 v36, v168, v10
	ds_bpermute_b32 v37, v168, v11
	s_waitcnt vmcnt(4) lgkmcnt(0)
	v_mov_b32_e32 v18, v206
	v_mov_b32_e32 v19, v207
	v_mov_b32_e32 v20, v208
	v_mov_b32_e32 v21, v209
	v_mov_b32_e32 v22, v210
	v_mov_b32_e32 v23, v211
	v_mov_b32_e32 v24, v212
	v_mov_b32_e32 v25, v213
	v_mov_b32_e32 v26, v214
	v_mov_b32_e32 v27, v215
	v_mov_b32_e32 v28, v216
	v_mov_b32_e32 v29, v217
	v_mov_b32_e32 v30, v218
	v_mov_b32_e32 v31, v219
	v_mov_b32_e32 v32, v220
	v_mov_b32_e32 v33, v221
	v_pk_mul_f32 v[26:27], v[26:27], v[36:37]
	v_pk_mul_f32 v[30:31], v[30:31], v[34:35]
	ds_bpermute_b32 v34, v168, v16
	ds_bpermute_b32 v35, v168, v17
	ds_bpermute_b32 v36, v168, v12
	ds_bpermute_b32 v37, v168, v13
	v_cndmask_b32_e64 v31, v31, -v31, s[46:47]
	v_cndmask_b32_e64 v30, v30, -v30, s[46:47]
	s_waitcnt lgkmcnt(2)
	v_pk_mul_f32 v[32:33], v[32:33], v[34:35]
	v_pk_fma_f32 v[14:15], v[14:15], v[22:23], v[30:31]
	v_cndmask_b32_e64 v33, v33, -v33, s[46:47]
	v_cndmask_b32_e64 v32, v32, -v32, s[46:47]
	s_waitcnt lgkmcnt(0)
	v_pk_mul_f32 v[22:23], v[28:29], v[36:37]
	v_pk_fma_f32 v[16:17], v[16:17], v[24:25], v[32:33]
	v_cndmask_b32_e64 v23, v23, -v23, s[46:47]
	v_cndmask_b32_e64 v22, v22, -v22, s[46:47]
	v_cndmask_b32_e64 v25, v27, -v27, s[46:47]
	v_cndmask_b32_e64 v24, v26, -v26, s[46:47]
	v_pk_fma_f32 v[12:13], v[12:13], v[20:21], v[22:23]
	v_pk_fma_f32 v[10:11], v[10:11], v[18:19], v[24:25]
.LBB0_614:
	v_mov_b32_e32 v77, v76
	v_cvt_pk_bf16_f32 v14, v14, v15
	v_cvt_pk_bf16_f32 v15, v16, v17
	v_cvt_pk_bf16_f32 v16, v10, v11
	v_mov_b32_e32 v10, v76
	v_mov_b32_e32 v11, v76
	v_cvt_pk_bf16_f32 v17, v12, v13
	v_pk_mul_f32 v[8:9], v[8:9], v[10:11]
	v_pk_mul_f32 v[6:7], v[6:7], v[76:77]
	v_pk_mul_f32 v[4:5], v[4:5], v[10:11]
	s_and_b64 vcc, exec, s[50:51]
	v_pk_mul_f32 v[2:3], v[2:3], v[76:77]
	global_store_dwordx4 v[78:79], v[14:17], off offset:256
	s_cbranch_vccnz .LBB0_616
	v_mov_b32_e32 v67, v1
	v_lshl_add_u64 v[22:23], v[148:149], 0, v[66:67]
	s_nop 0
	ds_bpermute_b32 v26, v168, v6
	ds_bpermute_b32 v27, v168, v7
	ds_bpermute_b32 v28, v168, v2
	ds_bpermute_b32 v29, v168, v3
	s_waitcnt vmcnt(0) lgkmcnt(0)
	v_mov_b32_e32 v10, v222
	v_mov_b32_e32 v11, v223
	v_mov_b32_e32 v12, v224
	v_mov_b32_e32 v13, v225
	v_mov_b32_e32 v14, v226
	v_mov_b32_e32 v15, v227
	v_mov_b32_e32 v16, v228
	v_mov_b32_e32 v17, v229
	v_mov_b32_e32 v18, v230
	v_mov_b32_e32 v19, v231
	v_mov_b32_e32 v20, v232
	v_mov_b32_e32 v21, v233
	v_mov_b32_e32 v22, v234
	v_mov_b32_e32 v23, v235
	v_mov_b32_e32 v24, v236
	v_mov_b32_e32 v25, v237
	v_pk_mul_f32 v[18:19], v[18:19], v[28:29]
	v_pk_mul_f32 v[22:23], v[22:23], v[26:27]
	ds_bpermute_b32 v26, v168, v8
	ds_bpermute_b32 v27, v168, v9
	ds_bpermute_b32 v28, v168, v4
	ds_bpermute_b32 v29, v168, v5
	v_cndmask_b32_e64 v23, v23, -v23, s[46:47]
	v_cndmask_b32_e64 v22, v22, -v22, s[46:47]
	s_waitcnt lgkmcnt(2)
	v_pk_mul_f32 v[24:25], v[24:25], v[26:27]
	v_pk_fma_f32 v[6:7], v[6:7], v[14:15], v[22:23]
	v_cndmask_b32_e64 v25, v25, -v25, s[46:47]
	v_cndmask_b32_e64 v24, v24, -v24, s[46:47]
	s_waitcnt lgkmcnt(0)
	v_pk_mul_f32 v[14:15], v[20:21], v[28:29]
	v_pk_fma_f32 v[8:9], v[8:9], v[16:17], v[24:25]
	v_cndmask_b32_e64 v15, v15, -v15, s[46:47]
	v_cndmask_b32_e64 v14, v14, -v14, s[46:47]
	v_cndmask_b32_e64 v17, v19, -v19, s[46:47]
	v_cndmask_b32_e64 v16, v18, -v18, s[46:47]
	v_pk_fma_f32 v[4:5], v[4:5], v[12:13], v[14:15]
	v_pk_fma_f32 v[2:3], v[2:3], v[10:11], v[16:17]
